# P5 merge: term-A gated bf16 rows 0-2 of each tile kept in spare VGPRs across the term-B unit instead of MB store+reload
# speedup vs baseline: 1.0089x; 1.0062x over previous
.LBB0_1269:
	s_cmp_lg_u32 s7, 0
	s_cselect_b64 s[4:5], -1, 0
	s_cmp_eq_u32 s7, 0
	s_cselect_b64 s[30:31], -1, 0
	s_and_b64 vcc, s[30:31], exec
	s_cselect_b32 s7, s54, 0x17800000
	s_add_u32 s30, s86, s7
	s_addc_u32 s31, s87, 0
	s_lshl_b32 s21, s6, 8
	v_lshl_or_b32 v138, s28, 8, v151
	v_add_u32_e32 v142, s21, v146
	v_ashrrev_i32_e32 v139, 31, v138
	v_ashrrev_i32_e32 v143, 31, v142
	v_lshl_add_u64 v[140:141], s[30:31], 0, v[138:139]
	v_lshlrev_b64 v[144:145], 10, v[142:143]
	v_lshl_add_u64 v[144:145], v[140:141], 0, v[144:145]
	global_load_dwordx4 v[156:159], v[144:145], off
	v_lshlrev_b64 v[144:145], 11, v[142:143]
	v_lshl_add_u64 v[144:145], s[10:11], 0, v[144:145]
	v_lshl_add_u64 v[144:145], v[138:139], 1, v[144:145]
	s_waitcnt vmcnt(0)
	v_cvt_f32_ubyte1_e32 v161, v156
	v_cvt_f32_ubyte0_e32 v160, v156
	v_cvt_f32_ubyte3_e32 v163, v156
	v_cvt_f32_ubyte2_e32 v162, v156
	v_cvt_f32_ubyte1_e32 v165, v157
	v_cvt_f32_ubyte0_e32 v164, v157
	v_cvt_f32_ubyte3_e32 v167, v157
	v_cvt_f32_ubyte2_e32 v166, v157
	v_cvt_f32_ubyte1_e32 v157, v158
	v_cvt_f32_ubyte0_e32 v156, v158
	v_cvt_f32_ubyte3_e32 v169, v158
	v_cvt_f32_ubyte2_e32 v168, v158
	v_cvt_f32_ubyte1_e32 v171, v159
	v_cvt_f32_ubyte0_e32 v170, v159
	v_cvt_f32_ubyte3_e32 v173, v159
	v_cvt_f32_ubyte2_e32 v172, v159
	v_pk_mul_f32 v[158:159], v[160:161], s[18:19] op_sel_hi:[1,0]
	v_pk_mul_f32 v[160:161], v[162:163], s[18:19] op_sel_hi:[1,0]
	v_pk_mul_f32 v[162:163], v[164:165], s[18:19] op_sel_hi:[1,0]
	v_pk_mul_f32 v[164:165], v[166:167], s[18:19] op_sel_hi:[1,0]
	v_pk_mul_f32 v[156:157], v[156:157], s[18:19] op_sel_hi:[1,0]
	v_pk_mul_f32 v[166:167], v[168:169], s[18:19] op_sel_hi:[1,0]
	v_pk_mul_f32 v[168:169], v[170:171], s[18:19] op_sel_hi:[1,0]
	v_pk_mul_f32 v[170:171], v[172:173], s[18:19] op_sel_hi:[1,0]
	v_pk_mul_f32 v[120:121], v[120:121], v[158:159]
	v_pk_mul_f32 v[122:123], v[122:123], v[160:161]
	v_pk_mul_f32 v[124:125], v[124:125], v[162:163]
	v_pk_mul_f32 v[126:127], v[126:127], v[164:165]
	v_pk_mul_f32 v[116:117], v[116:117], v[156:157]
	v_pk_mul_f32 v[118:119], v[118:119], v[166:167]
	v_pk_mul_f32 v[112:113], v[112:113], v[168:169]
	v_pk_mul_f32 v[114:115], v[114:115], v[170:171]
	s_cbranch_vccnz .LBB0_1271
	v_mov_b64_e32 v[156:157], v[224:225]
	v_mov_b64_e32 v[158:159], v[226:227]
	v_mov_b64_e32 v[160:161], v[228:229]
	v_mov_b64_e32 v[162:163], v[230:231]
	s_waitcnt vmcnt(0)
	v_lshlrev_b32_e32 v164, 16, v156
	v_and_b32_e32 v165, 0xffff0000, v156
	v_lshlrev_b32_e32 v156, 16, v157
	v_and_b32_e32 v157, 0xffff0000, v157
	v_lshlrev_b32_e32 v166, 16, v158
	v_and_b32_e32 v167, 0xffff0000, v158
	v_lshlrev_b32_e32 v158, 16, v159
	v_and_b32_e32 v159, 0xffff0000, v159
	v_lshlrev_b32_e32 v168, 16, v160
	v_and_b32_e32 v169, 0xffff0000, v160
	v_lshlrev_b32_e32 v160, 16, v161
	v_and_b32_e32 v161, 0xffff0000, v161
	v_lshlrev_b32_e32 v170, 16, v162
	v_and_b32_e32 v171, 0xffff0000, v162
	v_lshlrev_b32_e32 v162, 16, v163
	v_and_b32_e32 v163, 0xffff0000, v163
	v_pk_add_f32 v[120:121], v[120:121], v[164:165]
	v_pk_add_f32 v[122:123], v[122:123], v[156:157]
	v_pk_add_f32 v[124:125], v[124:125], v[166:167]
	v_pk_add_f32 v[126:127], v[126:127], v[158:159]
	v_pk_add_f32 v[116:117], v[116:117], v[168:169]
	v_pk_add_f32 v[118:119], v[118:119], v[160:161]
	v_pk_add_f32 v[112:113], v[112:113], v[170:171]
	v_pk_add_f32 v[114:115], v[114:115], v[162:163]
.LBB0_1271:
	v_cvt_pk_bf16_f32 v120, v120, v121
	v_cvt_pk_bf16_f32 v121, v122, v123
	v_cvt_pk_bf16_f32 v122, v124, v125
	v_cvt_pk_bf16_f32 v123, v126, v127
	v_cvt_pk_bf16_f32 v116, v116, v117
	v_cvt_pk_bf16_f32 v117, v118, v119
	v_cvt_pk_bf16_f32 v118, v112, v113
	v_cvt_pk_bf16_f32 v119, v114, v115
	s_andn2_b64 vcc, exec, s[4:5]
	s_cbranch_vccz .Lp5st_0
	v_mov_b64_e32 v[224:225], v[120:121]
	v_mov_b64_e32 v[226:227], v[122:123]
	v_mov_b64_e32 v[228:229], v[116:117]
	v_mov_b64_e32 v[230:231], v[118:119]
	s_branch .Lp5sk_0
.Lp5st_0:
	global_store_dwordx4 v[144:145], v[120:123], off
	global_store_dwordx4 v[144:145], v[116:119], off offset:16
.Lp5sk_0:
	s_andn2_b64 vcc, exec, s[4:5]
	s_nop 0
	v_add_u32_e32 v116, s21, v148
	v_ashrrev_i32_e32 v117, 31, v116
	v_lshlrev_b64 v[112:113], 10, v[116:117]
	v_lshl_add_u64 v[112:113], v[140:141], 0, v[112:113]
	global_load_dwordx4 v[112:115], v[112:113], off
	v_cndmask_b32_e64 v118, 0, 1, s[4:5]
	v_cmp_ne_u32_e64 s[6:7], 1, v118
	v_lshlrev_b64 v[116:117], 11, v[116:117]
	v_lshl_add_u64 v[116:117], s[10:11], 0, v[116:117]
	s_waitcnt vmcnt(0)
	v_cvt_f32_ubyte1_e32 v119, v112
	v_cvt_f32_ubyte0_e32 v118, v112
	v_cvt_f32_ubyte3_e32 v121, v112
	v_cvt_f32_ubyte2_e32 v120, v112
	v_cvt_f32_ubyte1_e32 v123, v113
	v_cvt_f32_ubyte0_e32 v122, v113
	v_cvt_f32_ubyte3_e32 v125, v113
	v_cvt_f32_ubyte2_e32 v124, v113
	v_cvt_f32_ubyte1_e32 v113, v114
	v_cvt_f32_ubyte0_e32 v112, v114
	v_cvt_f32_ubyte3_e32 v127, v114
	v_cvt_f32_ubyte2_e32 v126, v114
	v_cvt_f32_ubyte1_e32 v145, v115
	v_cvt_f32_ubyte0_e32 v144, v115
	v_cvt_f32_ubyte3_e32 v157, v115
	v_cvt_f32_ubyte2_e32 v156, v115
	v_pk_mul_f32 v[114:115], v[118:119], s[18:19] op_sel_hi:[1,0]
	v_pk_mul_f32 v[118:119], v[120:121], s[18:19] op_sel_hi:[1,0]
	v_pk_mul_f32 v[120:121], v[122:123], s[18:19] op_sel_hi:[1,0]
	v_pk_mul_f32 v[122:123], v[124:125], s[18:19] op_sel_hi:[1,0]
	v_pk_mul_f32 v[124:125], v[112:113], s[18:19] op_sel_hi:[1,0]
	v_pk_mul_f32 v[126:127], v[126:127], s[18:19] op_sel_hi:[1,0]
	v_pk_mul_f32 v[144:145], v[144:145], s[18:19] op_sel_hi:[1,0]
	v_pk_mul_f32 v[156:157], v[156:157], s[18:19] op_sel_hi:[1,0]
	v_pk_mul_f32 v[108:109], v[108:109], v[114:115]
	v_pk_mul_f32 v[110:111], v[110:111], v[118:119]
	v_pk_mul_f32 v[112:113], v[104:105], v[120:121]
	v_pk_mul_f32 v[106:107], v[106:107], v[122:123]
	v_pk_mul_f32 v[104:105], v[100:101], v[124:125]
	v_pk_mul_f32 v[102:103], v[102:103], v[126:127]
	v_pk_mul_f32 v[100:101], v[96:97], v[144:145]
	v_pk_mul_f32 v[98:99], v[98:99], v[156:157]
	v_lshl_add_u64 v[96:97], v[138:139], 1, v[116:117]
	s_cbranch_vccnz .LBB0_1273
	v_mov_b64_e32 v[114:115], v[232:233]
	v_mov_b64_e32 v[116:117], v[234:235]
	v_mov_b64_e32 v[118:119], v[236:237]
	v_mov_b64_e32 v[120:121], v[238:239]
	s_waitcnt vmcnt(0)
	v_lshlrev_b32_e32 v122, 16, v114
	v_and_b32_e32 v123, 0xffff0000, v114
	v_lshlrev_b32_e32 v114, 16, v115
	v_and_b32_e32 v115, 0xffff0000, v115
	v_lshlrev_b32_e32 v124, 16, v116
	v_and_b32_e32 v125, 0xffff0000, v116
	v_lshlrev_b32_e32 v116, 16, v117
	v_and_b32_e32 v117, 0xffff0000, v117
	v_lshlrev_b32_e32 v126, 16, v118
	v_and_b32_e32 v127, 0xffff0000, v118
	v_lshlrev_b32_e32 v118, 16, v119
	v_and_b32_e32 v119, 0xffff0000, v119
	v_lshlrev_b32_e32 v144, 16, v120
	v_and_b32_e32 v145, 0xffff0000, v120
	v_lshlrev_b32_e32 v120, 16, v121
	v_and_b32_e32 v121, 0xffff0000, v121
	v_pk_add_f32 v[108:109], v[108:109], v[122:123]
	v_pk_add_f32 v[110:111], v[110:111], v[114:115]
	v_pk_add_f32 v[112:113], v[112:113], v[124:125]
	v_pk_add_f32 v[106:107], v[106:107], v[116:117]
	v_pk_add_f32 v[104:105], v[104:105], v[126:127]
	v_pk_add_f32 v[102:103], v[102:103], v[118:119]
	v_pk_add_f32 v[100:101], v[100:101], v[144:145]
	v_pk_add_f32 v[98:99], v[98:99], v[120:121]
.LBB0_1273:
	v_cvt_pk_bf16_f32 v108, v108, v109
	v_cvt_pk_bf16_f32 v109, v110, v111
	v_cvt_pk_bf16_f32 v111, v106, v107
	v_cvt_pk_bf16_f32 v106, v100, v101
	v_add_u32_e32 v100, s21, v149
	v_cvt_pk_bf16_f32 v110, v112, v113
	v_ashrrev_i32_e32 v101, 31, v100
	v_cvt_pk_bf16_f32 v104, v104, v105
	v_cvt_pk_bf16_f32 v105, v102, v103
	v_cvt_pk_bf16_f32 v107, v98, v99
	s_andn2_b64 vcc, exec, s[4:5]
	s_cbranch_vccz .Lp5st_1
	v_mov_b64_e32 v[232:233], v[108:109]
	v_mov_b64_e32 v[234:235], v[110:111]
	v_mov_b64_e32 v[236:237], v[104:105]
	v_mov_b64_e32 v[238:239], v[106:107]
	s_branch .Lp5sk_1
.Lp5st_1:
	global_store_dwordx4 v[96:97], v[108:111], off
	global_store_dwordx4 v[96:97], v[104:107], off offset:16
.Lp5sk_1:
	v_lshlrev_b64 v[96:97], 10, v[100:101]
	v_lshl_add_u64 v[96:97], v[140:141], 0, v[96:97]
	global_load_dwordx4 v[96:99], v[96:97], off
	v_lshlrev_b64 v[100:101], 11, v[100:101]
	v_lshl_add_u64 v[100:101], s[10:11], 0, v[100:101]
	s_and_b64 vcc, exec, s[6:7]
	s_waitcnt vmcnt(0)
	v_cvt_f32_ubyte1_e32 v103, v96
	v_cvt_f32_ubyte0_e32 v102, v96
	v_cvt_f32_ubyte3_e32 v105, v96
	v_cvt_f32_ubyte2_e32 v104, v96
	v_cvt_f32_ubyte1_e32 v107, v97
	v_cvt_f32_ubyte0_e32 v106, v97
	v_cvt_f32_ubyte3_e32 v109, v97
	v_cvt_f32_ubyte2_e32 v108, v97
	v_cvt_f32_ubyte1_e32 v97, v98
	v_cvt_f32_ubyte0_e32 v96, v98
	v_cvt_f32_ubyte3_e32 v111, v98
	v_cvt_f32_ubyte2_e32 v110, v98
	v_cvt_f32_ubyte1_e32 v113, v99
	v_cvt_f32_ubyte0_e32 v112, v99
	v_cvt_f32_ubyte3_e32 v115, v99
	v_cvt_f32_ubyte2_e32 v114, v99
	v_pk_mul_f32 v[98:99], v[102:103], s[18:19] op_sel_hi:[1,0]
	v_pk_mul_f32 v[102:103], v[104:105], s[18:19] op_sel_hi:[1,0]
	v_pk_mul_f32 v[104:105], v[106:107], s[18:19] op_sel_hi:[1,0]
	v_pk_mul_f32 v[106:107], v[108:109], s[18:19] op_sel_hi:[1,0]
	v_pk_mul_f32 v[108:109], v[96:97], s[18:19] op_sel_hi:[1,0]
	v_pk_mul_f32 v[110:111], v[110:111], s[18:19] op_sel_hi:[1,0]
	v_pk_mul_f32 v[112:113], v[112:113], s[18:19] op_sel_hi:[1,0]
	v_pk_mul_f32 v[114:115], v[114:115], s[18:19] op_sel_hi:[1,0]
	v_pk_mul_f32 v[92:93], v[92:93], v[98:99]
	v_pk_mul_f32 v[94:95], v[94:95], v[102:103]
	v_pk_mul_f32 v[96:97], v[88:89], v[104:105]
	v_pk_mul_f32 v[90:91], v[90:91], v[106:107]
	v_pk_mul_f32 v[88:89], v[84:85], v[108:109]
	v_pk_mul_f32 v[86:87], v[86:87], v[110:111]
	v_pk_mul_f32 v[84:85], v[80:81], v[112:113]
	v_pk_mul_f32 v[82:83], v[82:83], v[114:115]
	v_lshl_add_u64 v[80:81], v[138:139], 1, v[100:101]
	s_cbranch_vccnz .LBB0_1275
	v_mov_b64_e32 v[98:99], v[242:243]
	v_mov_b64_e32 v[100:101], v[244:245]
	v_mov_b64_e32 v[102:103], v[246:247]
	v_mov_b64_e32 v[104:105], v[248:249]
	s_waitcnt vmcnt(0)
	v_lshlrev_b32_e32 v106, 16, v98
	v_and_b32_e32 v107, 0xffff0000, v98
	v_lshlrev_b32_e32 v98, 16, v99
	v_and_b32_e32 v99, 0xffff0000, v99
	v_lshlrev_b32_e32 v108, 16, v100
	v_and_b32_e32 v109, 0xffff0000, v100
	v_lshlrev_b32_e32 v100, 16, v101
	v_and_b32_e32 v101, 0xffff0000, v101
	v_lshlrev_b32_e32 v110, 16, v102
	v_and_b32_e32 v111, 0xffff0000, v102
	v_lshlrev_b32_e32 v102, 16, v103
	v_and_b32_e32 v103, 0xffff0000, v103
	v_lshlrev_b32_e32 v112, 16, v104
	v_and_b32_e32 v113, 0xffff0000, v104
	v_lshlrev_b32_e32 v104, 16, v105
	v_and_b32_e32 v105, 0xffff0000, v105
	v_pk_add_f32 v[92:93], v[92:93], v[106:107]
	v_pk_add_f32 v[94:95], v[94:95], v[98:99]
	v_pk_add_f32 v[96:97], v[96:97], v[108:109]
	v_pk_add_f32 v[90:91], v[90:91], v[100:101]
	v_pk_add_f32 v[88:89], v[88:89], v[110:111]
	v_pk_add_f32 v[86:87], v[86:87], v[102:103]
	v_pk_add_f32 v[84:85], v[84:85], v[112:113]
	v_pk_add_f32 v[82:83], v[82:83], v[104:105]
.LBB0_1275:
	v_cvt_pk_bf16_f32 v92, v92, v93
	v_cvt_pk_bf16_f32 v93, v94, v95
	v_cvt_pk_bf16_f32 v95, v90, v91
	v_cvt_pk_bf16_f32 v90, v84, v85
	v_add_u32_e32 v84, s21, v150
	v_cvt_pk_bf16_f32 v94, v96, v97
	v_ashrrev_i32_e32 v85, 31, v84
	v_cvt_pk_bf16_f32 v88, v88, v89
	v_cvt_pk_bf16_f32 v89, v86, v87
	v_cvt_pk_bf16_f32 v91, v82, v83
	s_andn2_b64 vcc, exec, s[4:5]
	s_cbranch_vccz .Lp5st_2
	v_mov_b64_e32 v[242:243], v[92:93]
	v_mov_b64_e32 v[244:245], v[94:95]
	v_mov_b64_e32 v[246:247], v[88:89]
	v_mov_b64_e32 v[248:249], v[90:91]
	s_branch .Lp5sk_2
.Lp5st_2:
	global_store_dwordx4 v[80:81], v[92:95], off
	global_store_dwordx4 v[80:81], v[88:91], off offset:16
.Lp5sk_2:
	v_lshlrev_b64 v[80:81], 10, v[84:85]
	v_lshl_add_u64 v[80:81], v[140:141], 0, v[80:81]
	global_load_dwordx4 v[80:83], v[80:81], off
	v_lshlrev_b64 v[84:85], 11, v[84:85]
	v_lshl_add_u64 v[84:85], s[10:11], 0, v[84:85]
	s_and_b64 vcc, exec, s[6:7]
	s_waitcnt vmcnt(0)
	v_cvt_f32_ubyte1_e32 v87, v80
	v_cvt_f32_ubyte0_e32 v86, v80
	v_cvt_f32_ubyte3_e32 v89, v80
	v_cvt_f32_ubyte2_e32 v88, v80
	v_cvt_f32_ubyte1_e32 v91, v81
	v_cvt_f32_ubyte0_e32 v90, v81
	v_cvt_f32_ubyte3_e32 v93, v81
	v_cvt_f32_ubyte2_e32 v92, v81
	v_cvt_f32_ubyte1_e32 v81, v82
	v_cvt_f32_ubyte0_e32 v80, v82
	v_cvt_f32_ubyte3_e32 v95, v82
	v_cvt_f32_ubyte2_e32 v94, v82
	v_cvt_f32_ubyte1_e32 v97, v83
	v_cvt_f32_ubyte0_e32 v96, v83
	v_cvt_f32_ubyte3_e32 v99, v83
	v_cvt_f32_ubyte2_e32 v98, v83
	v_pk_mul_f32 v[82:83], v[86:87], s[18:19] op_sel_hi:[1,0]
	v_pk_mul_f32 v[86:87], v[88:89], s[18:19] op_sel_hi:[1,0]
	v_pk_mul_f32 v[88:89], v[90:91], s[18:19] op_sel_hi:[1,0]
	v_pk_mul_f32 v[90:91], v[92:93], s[18:19] op_sel_hi:[1,0]
	v_pk_mul_f32 v[92:93], v[80:81], s[18:19] op_sel_hi:[1,0]
	v_pk_mul_f32 v[94:95], v[94:95], s[18:19] op_sel_hi:[1,0]
	v_pk_mul_f32 v[96:97], v[96:97], s[18:19] op_sel_hi:[1,0]
	v_pk_mul_f32 v[98:99], v[98:99], s[18:19] op_sel_hi:[1,0]
	v_pk_mul_f32 v[76:77], v[76:77], v[82:83]
	v_pk_mul_f32 v[78:79], v[78:79], v[86:87]
	v_pk_mul_f32 v[80:81], v[72:73], v[88:89]
	v_pk_mul_f32 v[74:75], v[74:75], v[90:91]
	v_pk_mul_f32 v[72:73], v[68:69], v[92:93]
	v_pk_mul_f32 v[70:71], v[70:71], v[94:95]
	v_pk_mul_f32 v[68:69], v[64:65], v[96:97]
	v_pk_mul_f32 v[66:67], v[66:67], v[98:99]
	v_lshl_add_u64 v[64:65], v[138:139], 1, v[84:85]
	s_cbranch_vccnz .LBB0_1277
	global_load_dwordx4 v[82:85], v[64:65], off
	global_load_dwordx4 v[86:89], v[64:65], off offset:16
	s_waitcnt vmcnt(0)
	v_lshlrev_b32_e32 v90, 16, v82
	v_and_b32_e32 v91, 0xffff0000, v82
	v_lshlrev_b32_e32 v82, 16, v83
	v_and_b32_e32 v83, 0xffff0000, v83
	v_lshlrev_b32_e32 v92, 16, v84
	v_and_b32_e32 v93, 0xffff0000, v84
	v_lshlrev_b32_e32 v84, 16, v85
	v_and_b32_e32 v85, 0xffff0000, v85
	v_lshlrev_b32_e32 v94, 16, v86
	v_and_b32_e32 v95, 0xffff0000, v86
	v_lshlrev_b32_e32 v86, 16, v87
	v_and_b32_e32 v87, 0xffff0000, v87
	v_lshlrev_b32_e32 v96, 16, v88
	v_and_b32_e32 v97, 0xffff0000, v88
	v_lshlrev_b32_e32 v88, 16, v89
	v_and_b32_e32 v89, 0xffff0000, v89
	v_pk_add_f32 v[76:77], v[76:77], v[90:91]
	v_pk_add_f32 v[78:79], v[78:79], v[82:83]
	v_pk_add_f32 v[80:81], v[80:81], v[92:93]
	v_pk_add_f32 v[74:75], v[74:75], v[84:85]
	v_pk_add_f32 v[72:73], v[72:73], v[94:95]
	v_pk_add_f32 v[70:71], v[70:71], v[86:87]
	v_pk_add_f32 v[68:69], v[68:69], v[96:97]
	v_pk_add_f32 v[66:67], v[66:67], v[88:89]

	.amdhsa_kernel _Z10fwd_kernel4Args
		.amdhsa_group_segment_fixed_size 0
		.amdhsa_private_segment_fixed_size 0
		.amdhsa_kernarg_size 528
		.amdhsa_user_sgpr_count 2
		.amdhsa_user_sgpr_dispatch_ptr 0
		.amdhsa_user_sgpr_queue_ptr 0
		.amdhsa_user_sgpr_kernarg_segment_ptr 1
		.amdhsa_user_sgpr_dispatch_id 0
		.amdhsa_user_sgpr_kernarg_preload_length 0
		.amdhsa_user_sgpr_kernarg_preload_offset 0
		.amdhsa_user_sgpr_private_segment_size 0
		.amdhsa_uses_dynamic_stack 0
		.amdhsa_enable_private_segment 0
		.amdhsa_system_sgpr_workgroup_id_x 1
		.amdhsa_system_sgpr_workgroup_id_y 0
		.amdhsa_system_sgpr_workgroup_id_z 0
		.amdhsa_system_sgpr_workgroup_info 0
		.amdhsa_system_vgpr_workitem_id 2
		.amdhsa_next_free_vgpr 250
		.amdhsa_next_free_sgpr 102
		.amdhsa_accum_offset 252
		.amdhsa_reserve_vcc 1
		.amdhsa_float_round_mode_32 0
		.amdhsa_float_round_mode_16_64 0
		.amdhsa_float_denorm_mode_32 3
		.amdhsa_float_denorm_mode_16_64 3
		.amdhsa_dx10_clamp 1
		.amdhsa_ieee_mode 1
		.amdhsa_fp16_overflow 0
		.amdhsa_tg_split 0
		.amdhsa_exception_fp_ieee_invalid_op 0
		.amdhsa_exception_fp_denorm_src 0
		.amdhsa_exception_fp_ieee_div_zero 0
		.amdhsa_exception_fp_ieee_overflow 0
		.amdhsa_exception_fp_ieee_underflow 0
		.amdhsa_exception_fp_ieee_inexact 0
		.amdhsa_exception_int_div_zero 0
	.end_amdhsa_kernel

amdhsa.kernels:
  - .agpr_count:     0
    .args:
      - .offset:         0
        .size:           272
        .value_kind:     by_value
      - .offset:         272
        .size:           4
        .value_kind:     hidden_block_count_x
      - .offset:         276
        .size:           4
        .value_kind:     hidden_block_count_y
      - .offset:         280
        .size:           4
        .value_kind:     hidden_block_count_z
      - .offset:         284
        .size:           2
        .value_kind:     hidden_group_size_x
      - .offset:         286
        .size:           2
        .value_kind:     hidden_group_size_y
      - .offset:         288
        .size:           2
        .value_kind:     hidden_group_size_z
      - .offset:         290
        .size:           2
        .value_kind:     hidden_remainder_x
      - .offset:         292
        .size:           2
        .value_kind:     hidden_remainder_y
      - .offset:         294
        .size:           2
        .value_kind:     hidden_remainder_z
      - .offset:         312
        .size:           8
        .value_kind:     hidden_global_offset_x
      - .offset:         320
        .size:           8
        .value_kind:     hidden_global_offset_y
      - .offset:         328
        .size:           8
        .value_kind:     hidden_global_offset_z
      - .offset:         336
        .size:           2
        .value_kind:     hidden_grid_dims
      - .offset:         360
        .size:           8
        .value_kind:     hidden_multigrid_sync_arg
      - .offset:         392
        .size:           4
        .value_kind:     hidden_dynamic_lds_size
    .group_segment_fixed_size: 0
    .kernarg_segment_align: 8
    .kernarg_segment_size: 528
    .language:       OpenCL C
    .language_version:
      - 2
      - 0
    .max_flat_workgroup_size: 512
    .name:           _Z10fwd_kernel4Args
    .private_segment_fixed_size: 0
    .sgpr_count:     108
    .sgpr_spill_count: 67
    .symbol:         _Z10fwd_kernel4Args.kd
    .uniform_work_group_size: 1
    .uses_dynamic_stack: false
    .vgpr_count:     250
    .vgpr_spill_count: 0
    .wavefront_size: 64
